# top-k popcount accumulation rebalanced: 1 of 8 rows on the scalar unit, 7 on the vector unit in two chains
# baseline (speedup 1.0000x reference)
; #define TK_GRP(g) { const int c0 = __popcll(__ballot(u[4 * (g)] >= cand)), c1 = __popcll(__ballot(u[4 * (g) + 1] >= cand)), c2 = __popcll(__ballot(u[4 * (g) + 2] >= cand)), c3 = __popcll(__ballot(u[4 * (g) + 3] >= cand)); cnt += (c0 + c1) + (c2 + c3); }
; __device__ __forceinline__ void indexer_unit(const Args& a, LAS unsigned char* lds, LAS unsigned long long* maskl, int b, int qblk, int wave, int lane) {
;     ...
;             unsigned T = 0u; bool exact = false; const int ng = (nr + 3) >> 2;
; #pragma unroll 1
;     ...
;                 const unsigned cand = T | (1u << bit); int cnt = 0;
;     ...
;                 switch (ng) {
;                     case 8: TK_GRP(7) [[fallthrough]];
;                     case 7: TK_GRP(6) [[fallthrough]];
;                     case 6: TK_GRP(5) [[fallthrough]];
;                     case 5: TK_GRP(4) [[fallthrough]];
;                     case 4: TK_GRP(3) [[fallthrough]];
;                     case 3: TK_GRP(2) [[fallthrough]];
;                     case 2: TK_GRP(1) [[fallthrough]];
;                     default: TK_GRP(0)
;                 }
;     ...
;                 if (cnt >= 256) { T = cand; if (cnt == 256) { exact = true; break; } }
;             }
;             int need = 0; const unsigned long long lt = (1ull << lane) - 1ull;
;             if (!exact) {
;                 int cl = 0;
; #pragma unroll
;                 for (int r = 0; r < 32; ++r) cl += (u[r] > T) ? 1 : 0;
;                 int ngt = 0;
; #pragma unroll
;                 for (int bb = 0; bb < 6; ++bb) ngt += __popcll(__ballot((cl >> bb) & 1)) << bb;
;                 need = 256 - ngt;
.Ltk_bit:
	s_lshl_b32 s12, 1, s11
	s_or_b32 s13, s10, s12
	v_mov_b32_e32 v24, 0
	v_mov_b32_e32 v25, 0
	v_cmp_le_u32_e64 s[24:25], s13, v32
	v_cmp_le_u32_e64 s[26:27], s13, v33
	v_cmp_le_u32_e64 s[28:29], s13, v34
	v_cmp_le_u32_e64 s[30:31], s13, v35
	v_cmp_le_u32_e64 s[34:35], s13, v36
	v_cmp_le_u32_e64 s[36:37], s13, v37
	v_cmp_le_u32_e64 s[38:39], s13, v38
	v_cmp_le_u32_e64 s[40:41], s13, v39
	s_bcnt1_i32_b64 s42, s[24:25]
	s_bcnt1_i32_b64 s43, s[26:27]
	s_bcnt1_i32_b64 s44, s[28:29]
	s_bcnt1_i32_b64 s45, s[30:31]
	s_bcnt1_i32_b64 s46, s[34:35]
	s_bcnt1_i32_b64 s47, s[36:37]
	s_bcnt1_i32_b64 s48, s[38:39]
	s_bcnt1_i32_b64 s49, s[40:41]
	s_mov_b32 s14, s42
	v_add_u32_e32 v25, s43, v25
	v_add_u32_e32 v24, s44, v24
	v_add_u32_e32 v25, s45, v25
	v_add_u32_e32 v24, s46, v24
	v_add_u32_e32 v25, s47, v25
	v_add_u32_e32 v24, s48, v24
	v_add_u32_e32 v25, s49, v25
	s_cmp_lt_u32 s21, 2
	s_cbranch_scc1 .Ltk_dec
	v_cmp_le_u32_e64 s[24:25], s13, v40
	v_cmp_le_u32_e64 s[26:27], s13, v41
	v_cmp_le_u32_e64 s[28:29], s13, v42
	v_cmp_le_u32_e64 s[30:31], s13, v43
	v_cmp_le_u32_e64 s[34:35], s13, v44
	v_cmp_le_u32_e64 s[36:37], s13, v45
	v_cmp_le_u32_e64 s[38:39], s13, v46
	v_cmp_le_u32_e64 s[40:41], s13, v47
	s_bcnt1_i32_b64 s42, s[24:25]
	s_bcnt1_i32_b64 s43, s[26:27]
	s_bcnt1_i32_b64 s44, s[28:29]
	s_bcnt1_i32_b64 s45, s[30:31]
	s_bcnt1_i32_b64 s46, s[34:35]
	s_bcnt1_i32_b64 s47, s[36:37]
	s_bcnt1_i32_b64 s48, s[38:39]
	s_bcnt1_i32_b64 s49, s[40:41]
	s_add_i32 s14, s14, s42
	v_add_u32_e32 v25, s43, v25
	v_add_u32_e32 v24, s44, v24
	v_add_u32_e32 v25, s45, v25
	v_add_u32_e32 v24, s46, v24
	v_add_u32_e32 v25, s47, v25
	v_add_u32_e32 v24, s48, v24
	v_add_u32_e32 v25, s49, v25
	s_cmp_lt_u32 s21, 3
	s_cbranch_scc1 .Ltk_dec
	v_cmp_le_u32_e64 s[24:25], s13, v48
	v_cmp_le_u32_e64 s[26:27], s13, v49
	v_cmp_le_u32_e64 s[28:29], s13, v50
	v_cmp_le_u32_e64 s[30:31], s13, v51
	v_cmp_le_u32_e64 s[34:35], s13, v52
	v_cmp_le_u32_e64 s[36:37], s13, v53
	v_cmp_le_u32_e64 s[38:39], s13, v54
	v_cmp_le_u32_e64 s[40:41], s13, v55
	s_bcnt1_i32_b64 s42, s[24:25]
	s_bcnt1_i32_b64 s43, s[26:27]
	s_bcnt1_i32_b64 s44, s[28:29]
	s_bcnt1_i32_b64 s45, s[30:31]
	s_bcnt1_i32_b64 s46, s[34:35]
	s_bcnt1_i32_b64 s47, s[36:37]
	s_bcnt1_i32_b64 s48, s[38:39]
	s_bcnt1_i32_b64 s49, s[40:41]
	s_add_i32 s14, s14, s42
	v_add_u32_e32 v25, s43, v25
	v_add_u32_e32 v24, s44, v24
	v_add_u32_e32 v25, s45, v25
	v_add_u32_e32 v24, s46, v24
	v_add_u32_e32 v25, s47, v25
	v_add_u32_e32 v24, s48, v24
	v_add_u32_e32 v25, s49, v25
	s_cmp_lt_u32 s21, 4
	s_cbranch_scc1 .Ltk_dec
	v_cmp_le_u32_e64 s[24:25], s13, v56
	v_cmp_le_u32_e64 s[26:27], s13, v57
	v_cmp_le_u32_e64 s[28:29], s13, v58
	v_cmp_le_u32_e64 s[30:31], s13, v59
	v_cmp_le_u32_e64 s[34:35], s13, v60
	v_cmp_le_u32_e64 s[36:37], s13, v61
	v_cmp_le_u32_e64 s[38:39], s13, v62
	v_cmp_le_u32_e64 s[40:41], s13, v63
	s_bcnt1_i32_b64 s42, s[24:25]
	s_bcnt1_i32_b64 s43, s[26:27]
	s_bcnt1_i32_b64 s44, s[28:29]
	s_bcnt1_i32_b64 s45, s[30:31]
	s_bcnt1_i32_b64 s46, s[34:35]
	s_bcnt1_i32_b64 s47, s[36:37]
	s_bcnt1_i32_b64 s48, s[38:39]
	s_bcnt1_i32_b64 s49, s[40:41]
	s_add_i32 s14, s14, s42
	v_add_u32_e32 v25, s43, v25
	v_add_u32_e32 v24, s44, v24
	v_add_u32_e32 v25, s45, v25
	v_add_u32_e32 v24, s46, v24
	v_add_u32_e32 v25, s47, v25
	v_add_u32_e32 v24, s48, v24
	v_add_u32_e32 v25, s49, v25
.Ltk_dec:
	v_add_u32_e32 v24, v24, v25
	s_nop 0
	v_readfirstlane_b32 s15, v24
	s_add_i32 s14, s14, s15
	s_cmpk_lt_u32 s14, 0x100
	s_cbranch_scc1 .Ltk_nxt
	s_mov_b32 s10, s13
	s_cmpk_eq_u32 s14, 0x100
	s_cbranch_scc1 .Ltk_exact
.Ltk_nxt:
	s_add_i32 s11, s11, -1
	s_cmp_ge_i32 s11, 0
	s_cbranch_scc1 .Ltk_bit
	v_mov_b32_e32 v100, 0
	v_mov_b32_e32 v101, 0
	v_mov_b32_e32 v24, 0
	v_mov_b32_e32 v25, 0
	v_cmp_lt_u32_e64 s[24:25], s10, v32
	v_cmp_lt_u32_e64 s[26:27], s10, v33
	v_cmp_lt_u32_e64 s[28:29], s10, v34
	v_cmp_lt_u32_e64 s[30:31], s10, v35
	v_cmp_lt_u32_e64 s[34:35], s10, v36
	v_cmp_lt_u32_e64 s[36:37], s10, v37
	v_cmp_lt_u32_e64 s[38:39], s10, v38
	v_cmp_lt_u32_e64 s[40:41], s10, v39
	s_bcnt1_i32_b64 s42, s[24:25]
	s_bcnt1_i32_b64 s43, s[26:27]
	s_bcnt1_i32_b64 s44, s[28:29]
	s_bcnt1_i32_b64 s45, s[30:31]
	s_bcnt1_i32_b64 s46, s[34:35]
	s_bcnt1_i32_b64 s47, s[36:37]
	s_bcnt1_i32_b64 s48, s[38:39]
	s_bcnt1_i32_b64 s49, s[40:41]
	s_mov_b32 s14, s42
	v_add_u32_e32 v25, s43, v25
	v_add_u32_e32 v24, s44, v24
	v_add_u32_e32 v25, s45, v25
	v_add_u32_e32 v24, s46, v24
	v_add_u32_e32 v25, s47, v25
	v_add_u32_e32 v24, s48, v24
	v_add_u32_e32 v25, s49, v25
	s_cmp_lt_u32 s21, 2
	s_cbranch_scc1 .Ltk_tie_cnt_done
	v_cmp_lt_u32_e64 s[24:25], s10, v40
	v_cmp_lt_u32_e64 s[26:27], s10, v41
	v_cmp_lt_u32_e64 s[28:29], s10, v42
	v_cmp_lt_u32_e64 s[30:31], s10, v43
	v_cmp_lt_u32_e64 s[34:35], s10, v44
	v_cmp_lt_u32_e64 s[36:37], s10, v45
	v_cmp_lt_u32_e64 s[38:39], s10, v46
	v_cmp_lt_u32_e64 s[40:41], s10, v47
	s_bcnt1_i32_b64 s42, s[24:25]
	s_bcnt1_i32_b64 s43, s[26:27]
	s_bcnt1_i32_b64 s44, s[28:29]
	s_bcnt1_i32_b64 s45, s[30:31]
	s_bcnt1_i32_b64 s46, s[34:35]
	s_bcnt1_i32_b64 s47, s[36:37]
	s_bcnt1_i32_b64 s48, s[38:39]
	s_bcnt1_i32_b64 s49, s[40:41]
	s_add_i32 s14, s14, s42
	v_add_u32_e32 v25, s43, v25
	v_add_u32_e32 v24, s44, v24
	v_add_u32_e32 v25, s45, v25
	v_add_u32_e32 v24, s46, v24
	v_add_u32_e32 v25, s47, v25
	v_add_u32_e32 v24, s48, v24
	v_add_u32_e32 v25, s49, v25
	s_cmp_lt_u32 s21, 3
	s_cbranch_scc1 .Ltk_tie_cnt_done
	v_cmp_lt_u32_e64 s[24:25], s10, v48
	v_cmp_lt_u32_e64 s[26:27], s10, v49
	v_cmp_lt_u32_e64 s[28:29], s10, v50
	v_cmp_lt_u32_e64 s[30:31], s10, v51
	v_cmp_lt_u32_e64 s[34:35], s10, v52
	v_cmp_lt_u32_e64 s[36:37], s10, v53
	v_cmp_lt_u32_e64 s[38:39], s10, v54
	v_cmp_lt_u32_e64 s[40:41], s10, v55
	s_bcnt1_i32_b64 s42, s[24:25]
	s_bcnt1_i32_b64 s43, s[26:27]
	s_bcnt1_i32_b64 s44, s[28:29]
	s_bcnt1_i32_b64 s45, s[30:31]
	s_bcnt1_i32_b64 s46, s[34:35]
	s_bcnt1_i32_b64 s47, s[36:37]
	s_bcnt1_i32_b64 s48, s[38:39]
	s_bcnt1_i32_b64 s49, s[40:41]
	s_add_i32 s14, s14, s42
	v_add_u32_e32 v25, s43, v25
	v_add_u32_e32 v24, s44, v24
	v_add_u32_e32 v25, s45, v25
	v_add_u32_e32 v24, s46, v24
	v_add_u32_e32 v25, s47, v25
	v_add_u32_e32 v24, s48, v24
	v_add_u32_e32 v25, s49, v25
	s_cmp_lt_u32 s21, 4
	s_cbranch_scc1 .Ltk_tie_cnt_done
	v_cmp_lt_u32_e64 s[24:25], s10, v56
	v_cmp_lt_u32_e64 s[26:27], s10, v57
	v_cmp_lt_u32_e64 s[28:29], s10, v58
	v_cmp_lt_u32_e64 s[30:31], s10, v59
	v_cmp_lt_u32_e64 s[34:35], s10, v60
	v_cmp_lt_u32_e64 s[36:37], s10, v61
	v_cmp_lt_u32_e64 s[38:39], s10, v62
	v_cmp_lt_u32_e64 s[40:41], s10, v63
	s_bcnt1_i32_b64 s42, s[24:25]
	s_bcnt1_i32_b64 s43, s[26:27]
	s_bcnt1_i32_b64 s44, s[28:29]
	s_bcnt1_i32_b64 s45, s[30:31]
	s_bcnt1_i32_b64 s46, s[34:35]
	s_bcnt1_i32_b64 s47, s[36:37]
	s_bcnt1_i32_b64 s48, s[38:39]
	s_bcnt1_i32_b64 s49, s[40:41]
	s_add_i32 s14, s14, s42
	v_add_u32_e32 v25, s43, v25
	v_add_u32_e32 v24, s44, v24
	v_add_u32_e32 v25, s45, v25
	v_add_u32_e32 v24, s46, v24
	v_add_u32_e32 v25, s47, v25
	v_add_u32_e32 v24, s48, v24
	v_add_u32_e32 v25, s49, v25
; __device__ __forceinline__ void indexer_unit(const Args& a, LAS unsigned char* lds, LAS unsigned long long* maskl, int b, int qblk, int wave, int lane) {
;     ...
;             int need = 0; const unsigned long long lt = (1ull << lane) - 1ull;
;             if (!exact) {
;                 int cl = 0;
; #pragma unroll
;                 for (int r = 0; r < 32; ++r) cl += (u[r] > T) ? 1 : 0;
;                 int ngt = 0;
; #pragma unroll
;                 for (int bb = 0; bb < 6; ++bb) ngt += __popcll(__ballot((cl >> bb) & 1)) << bb;
;                 need = 256 - ngt;
;             }
; #pragma unroll
;             for (int g = 0; g < 8; ++g) if (4 * g < nr) {
; #pragma unroll
;                 for (int k = 0; k < 4; ++k) { const int r = 4 * g + k;
;                     unsigned ur = u[r]; asm volatile("" : "+v"(ur), "+v"(myword), "+s"(need));
;                     unsigned long long m;
;                     if (exact) m = __ballot(ur >= T);
;                     else { const unsigned long long eq = __ballot(ur == T), gt = __ballot(ur > T);
;                         const bool pick = (ur == T) && (__popcll(eq & lt) < need);
;                         m = gt | __ballot(pick); need -= __popcll(eq); if (need < 0) need = 0; }
;                     if (lane == r) myword = m; } }
.Ltk_tie_cnt_done:
	v_add_u32_e32 v24, v24, v25
	s_nop 0
	v_readfirstlane_b32 s15, v24
	s_add_i32 s14, s14, s15
	s_sub_i32 s16, 0x100, s14
	v_cmp_eq_u32_e64 s[24:25], s10, v32
	v_cmp_lt_u32_e64 s[26:27], s10, v32
	s_bcnt1_i32_b64 s17, s[24:25]
	s_nop 0
	v_mbcnt_lo_u32_b32 v99, s24, 0
	v_mbcnt_hi_u32_b32 v99, s25, v99
	v_cmp_gt_u32_e64 s[28:29], s16, v99
	s_and_b64 s[28:29], s[28:29], s[24:25]
	s_or_b64 s[26:27], s[26:27], s[28:29]
	s_sub_i32 s16, s16, s17
	s_max_i32 s16, s16, 0
	v_writelane_b32 v100, s26, 0
	v_writelane_b32 v101, s27, 0
	v_cmp_eq_u32_e64 s[24:25], s10, v33
	v_cmp_lt_u32_e64 s[26:27], s10, v33
	s_bcnt1_i32_b64 s17, s[24:25]
	s_nop 0
	v_mbcnt_lo_u32_b32 v99, s24, 0
	v_mbcnt_hi_u32_b32 v99, s25, v99
	v_cmp_gt_u32_e64 s[28:29], s16, v99
	s_and_b64 s[28:29], s[28:29], s[24:25]
	s_or_b64 s[26:27], s[26:27], s[28:29]
	s_sub_i32 s16, s16, s17
	s_max_i32 s16, s16, 0
	v_writelane_b32 v100, s26, 1
	v_writelane_b32 v101, s27, 1
	v_cmp_eq_u32_e64 s[24:25], s10, v34
	v_cmp_lt_u32_e64 s[26:27], s10, v34
	s_bcnt1_i32_b64 s17, s[24:25]
	s_nop 0
	v_mbcnt_lo_u32_b32 v99, s24, 0
	v_mbcnt_hi_u32_b32 v99, s25, v99
	v_cmp_gt_u32_e64 s[28:29], s16, v99
	s_and_b64 s[28:29], s[28:29], s[24:25]
	s_or_b64 s[26:27], s[26:27], s[28:29]
	s_sub_i32 s16, s16, s17
	s_max_i32 s16, s16, 0
	v_writelane_b32 v100, s26, 2
	v_writelane_b32 v101, s27, 2
	v_cmp_eq_u32_e64 s[24:25], s10, v35
	v_cmp_lt_u32_e64 s[26:27], s10, v35
	s_bcnt1_i32_b64 s17, s[24:25]
	s_nop 0
	v_mbcnt_lo_u32_b32 v99, s24, 0
	v_mbcnt_hi_u32_b32 v99, s25, v99
	v_cmp_gt_u32_e64 s[28:29], s16, v99
	s_and_b64 s[28:29], s[28:29], s[24:25]
	s_or_b64 s[26:27], s[26:27], s[28:29]
	s_sub_i32 s16, s16, s17
	s_max_i32 s16, s16, 0
	v_writelane_b32 v100, s26, 3
	v_writelane_b32 v101, s27, 3
	v_cmp_eq_u32_e64 s[24:25], s10, v36
	v_cmp_lt_u32_e64 s[26:27], s10, v36
	s_bcnt1_i32_b64 s17, s[24:25]
	s_nop 0
	v_mbcnt_lo_u32_b32 v99, s24, 0
	v_mbcnt_hi_u32_b32 v99, s25, v99
	v_cmp_gt_u32_e64 s[28:29], s16, v99
	s_and_b64 s[28:29], s[28:29], s[24:25]
	s_or_b64 s[26:27], s[26:27], s[28:29]
	s_sub_i32 s16, s16, s17
	s_max_i32 s16, s16, 0
	v_writelane_b32 v100, s26, 4
	v_writelane_b32 v101, s27, 4
	v_cmp_eq_u32_e64 s[24:25], s10, v37
	v_cmp_lt_u32_e64 s[26:27], s10, v37
	s_bcnt1_i32_b64 s17, s[24:25]
	s_nop 0
	v_mbcnt_lo_u32_b32 v99, s24, 0
	v_mbcnt_hi_u32_b32 v99, s25, v99
	v_cmp_gt_u32_e64 s[28:29], s16, v99
	s_and_b64 s[28:29], s[28:29], s[24:25]
	s_or_b64 s[26:27], s[26:27], s[28:29]
	s_sub_i32 s16, s16, s17
	s_max_i32 s16, s16, 0
	v_writelane_b32 v100, s26, 5
	v_writelane_b32 v101, s27, 5
	v_cmp_eq_u32_e64 s[24:25], s10, v38
	v_cmp_lt_u32_e64 s[26:27], s10, v38
	s_bcnt1_i32_b64 s17, s[24:25]
	s_nop 0
	v_mbcnt_lo_u32_b32 v99, s24, 0
	v_mbcnt_hi_u32_b32 v99, s25, v99
	v_cmp_gt_u32_e64 s[28:29], s16, v99
	s_and_b64 s[28:29], s[28:29], s[24:25]
	s_or_b64 s[26:27], s[26:27], s[28:29]
	s_sub_i32 s16, s16, s17
	s_max_i32 s16, s16, 0
	v_writelane_b32 v100, s26, 6
	v_writelane_b32 v101, s27, 6
	v_cmp_eq_u32_e64 s[24:25], s10, v39
	v_cmp_lt_u32_e64 s[26:27], s10, v39
	s_bcnt1_i32_b64 s17, s[24:25]
	s_nop 0
	v_mbcnt_lo_u32_b32 v99, s24, 0
	v_mbcnt_hi_u32_b32 v99, s25, v99
	v_cmp_gt_u32_e64 s[28:29], s16, v99
	s_and_b64 s[28:29], s[28:29], s[24:25]
	s_or_b64 s[26:27], s[26:27], s[28:29]
	s_sub_i32 s16, s16, s17
	s_max_i32 s16, s16, 0
	v_writelane_b32 v100, s26, 7
	v_writelane_b32 v101, s27, 7
	s_cmp_lt_u32 s21, 2
	s_cbranch_scc1 .Ltk_store
	v_cmp_eq_u32_e64 s[24:25], s10, v40
	v_cmp_lt_u32_e64 s[26:27], s10, v40
	s_bcnt1_i32_b64 s17, s[24:25]
	s_nop 0
	v_mbcnt_lo_u32_b32 v99, s24, 0
	v_mbcnt_hi_u32_b32 v99, s25, v99
	v_cmp_gt_u32_e64 s[28:29], s16, v99
	s_and_b64 s[28:29], s[28:29], s[24:25]
	s_or_b64 s[26:27], s[26:27], s[28:29]
	s_sub_i32 s16, s16, s17
	s_max_i32 s16, s16, 0
	v_writelane_b32 v100, s26, 8
	v_writelane_b32 v101, s27, 8
	v_cmp_eq_u32_e64 s[24:25], s10, v41
	v_cmp_lt_u32_e64 s[26:27], s10, v41
	s_bcnt1_i32_b64 s17, s[24:25]
	s_nop 0
	v_mbcnt_lo_u32_b32 v99, s24, 0
	v_mbcnt_hi_u32_b32 v99, s25, v99
	v_cmp_gt_u32_e64 s[28:29], s16, v99
	s_and_b64 s[28:29], s[28:29], s[24:25]
	s_or_b64 s[26:27], s[26:27], s[28:29]
	s_sub_i32 s16, s16, s17
	s_max_i32 s16, s16, 0
	v_writelane_b32 v100, s26, 9
	v_writelane_b32 v101, s27, 9
	v_cmp_eq_u32_e64 s[24:25], s10, v42
	v_cmp_lt_u32_e64 s[26:27], s10, v42
	s_bcnt1_i32_b64 s17, s[24:25]
	s_nop 0
	v_mbcnt_lo_u32_b32 v99, s24, 0
	v_mbcnt_hi_u32_b32 v99, s25, v99
	v_cmp_gt_u32_e64 s[28:29], s16, v99
	s_and_b64 s[28:29], s[28:29], s[24:25]
	s_or_b64 s[26:27], s[26:27], s[28:29]
	s_sub_i32 s16, s16, s17
	s_max_i32 s16, s16, 0
	v_writelane_b32 v100, s26, 10
	v_writelane_b32 v101, s27, 10
	v_cmp_eq_u32_e64 s[24:25], s10, v43
	v_cmp_lt_u32_e64 s[26:27], s10, v43
	s_bcnt1_i32_b64 s17, s[24:25]
	s_nop 0
	v_mbcnt_lo_u32_b32 v99, s24, 0
	v_mbcnt_hi_u32_b32 v99, s25, v99
	v_cmp_gt_u32_e64 s[28:29], s16, v99
	s_and_b64 s[28:29], s[28:29], s[24:25]
	s_or_b64 s[26:27], s[26:27], s[28:29]
	s_sub_i32 s16, s16, s17
	s_max_i32 s16, s16, 0
	v_writelane_b32 v100, s26, 11
	v_writelane_b32 v101, s27, 11
	v_cmp_eq_u32_e64 s[24:25], s10, v44
	v_cmp_lt_u32_e64 s[26:27], s10, v44
	s_bcnt1_i32_b64 s17, s[24:25]
	s_nop 0
	v_mbcnt_lo_u32_b32 v99, s24, 0
	v_mbcnt_hi_u32_b32 v99, s25, v99
	v_cmp_gt_u32_e64 s[28:29], s16, v99
	s_and_b64 s[28:29], s[28:29], s[24:25]
	s_or_b64 s[26:27], s[26:27], s[28:29]
	s_sub_i32 s16, s16, s17
	s_max_i32 s16, s16, 0
	v_writelane_b32 v100, s26, 12
	v_writelane_b32 v101, s27, 12
	v_cmp_eq_u32_e64 s[24:25], s10, v45
	v_cmp_lt_u32_e64 s[26:27], s10, v45
	s_bcnt1_i32_b64 s17, s[24:25]
	s_nop 0
	v_mbcnt_lo_u32_b32 v99, s24, 0
	v_mbcnt_hi_u32_b32 v99, s25, v99
	v_cmp_gt_u32_e64 s[28:29], s16, v99
	s_and_b64 s[28:29], s[28:29], s[24:25]
	s_or_b64 s[26:27], s[26:27], s[28:29]
	s_sub_i32 s16, s16, s17
	s_max_i32 s16, s16, 0
	v_writelane_b32 v100, s26, 13
	v_writelane_b32 v101, s27, 13
	v_cmp_eq_u32_e64 s[24:25], s10, v46
	v_cmp_lt_u32_e64 s[26:27], s10, v46
	s_bcnt1_i32_b64 s17, s[24:25]
	s_nop 0
	v_mbcnt_lo_u32_b32 v99, s24, 0
	v_mbcnt_hi_u32_b32 v99, s25, v99
	v_cmp_gt_u32_e64 s[28:29], s16, v99
	s_and_b64 s[28:29], s[28:29], s[24:25]
	s_or_b64 s[26:27], s[26:27], s[28:29]
	s_sub_i32 s16, s16, s17
	s_max_i32 s16, s16, 0
	v_writelane_b32 v100, s26, 14
	v_writelane_b32 v101, s27, 14
	v_cmp_eq_u32_e64 s[24:25], s10, v47
	v_cmp_lt_u32_e64 s[26:27], s10, v47
	s_bcnt1_i32_b64 s17, s[24:25]
	s_nop 0
	v_mbcnt_lo_u32_b32 v99, s24, 0
	v_mbcnt_hi_u32_b32 v99, s25, v99
	v_cmp_gt_u32_e64 s[28:29], s16, v99
	s_and_b64 s[28:29], s[28:29], s[24:25]
	s_or_b64 s[26:27], s[26:27], s[28:29]
	s_sub_i32 s16, s16, s17
	s_max_i32 s16, s16, 0
	v_writelane_b32 v100, s26, 15
	v_writelane_b32 v101, s27, 15
	s_cmp_lt_u32 s21, 3
	s_cbranch_scc1 .Ltk_store
; __device__ __forceinline__ void indexer_unit(const Args& a, LAS unsigned char* lds, LAS unsigned long long* maskl, int b, int qblk, int wave, int lane) {
;     ...
; #pragma unroll
;             for (int g = 0; g < 8; ++g) if (4 * g < nr) {
; #pragma unroll
;                 for (int k = 0; k < 4; ++k) { const int r = 4 * g + k;
;                     unsigned ur = u[r]; asm volatile("" : "+v"(ur), "+v"(myword), "+s"(need));
;                     unsigned long long m;
;                     if (exact) m = __ballot(ur >= T);
;                     else { const unsigned long long eq = __ballot(ur == T), gt = __ballot(ur > T);
;                         const bool pick = (ur == T) && (__popcll(eq & lt) < need);
;                         m = gt | __ballot(pick); need -= __popcll(eq); if (need < 0) need = 0; }
;                     if (lane == r) myword = m; } }
;         }
;         if (lane < 32) maskl[q * 32 + lane] = myword;
	v_cmp_eq_u32_e64 s[24:25], s10, v48
	v_cmp_lt_u32_e64 s[26:27], s10, v48
	s_bcnt1_i32_b64 s17, s[24:25]
	s_nop 0
	v_mbcnt_lo_u32_b32 v99, s24, 0
	v_mbcnt_hi_u32_b32 v99, s25, v99
	v_cmp_gt_u32_e64 s[28:29], s16, v99
	s_and_b64 s[28:29], s[28:29], s[24:25]
	s_or_b64 s[26:27], s[26:27], s[28:29]
	s_sub_i32 s16, s16, s17
	s_max_i32 s16, s16, 0
	v_writelane_b32 v100, s26, 16
	v_writelane_b32 v101, s27, 16
	v_cmp_eq_u32_e64 s[24:25], s10, v49
	v_cmp_lt_u32_e64 s[26:27], s10, v49
	s_bcnt1_i32_b64 s17, s[24:25]
	s_nop 0
	v_mbcnt_lo_u32_b32 v99, s24, 0
	v_mbcnt_hi_u32_b32 v99, s25, v99
	v_cmp_gt_u32_e64 s[28:29], s16, v99
	s_and_b64 s[28:29], s[28:29], s[24:25]
	s_or_b64 s[26:27], s[26:27], s[28:29]
	s_sub_i32 s16, s16, s17
	s_max_i32 s16, s16, 0
	v_writelane_b32 v100, s26, 17
	v_writelane_b32 v101, s27, 17
	v_cmp_eq_u32_e64 s[24:25], s10, v50
	v_cmp_lt_u32_e64 s[26:27], s10, v50
	s_bcnt1_i32_b64 s17, s[24:25]
	s_nop 0
	v_mbcnt_lo_u32_b32 v99, s24, 0
	v_mbcnt_hi_u32_b32 v99, s25, v99
	v_cmp_gt_u32_e64 s[28:29], s16, v99
	s_and_b64 s[28:29], s[28:29], s[24:25]
	s_or_b64 s[26:27], s[26:27], s[28:29]
	s_sub_i32 s16, s16, s17
	s_max_i32 s16, s16, 0
	v_writelane_b32 v100, s26, 18
	v_writelane_b32 v101, s27, 18
	v_cmp_eq_u32_e64 s[24:25], s10, v51
	v_cmp_lt_u32_e64 s[26:27], s10, v51
	s_bcnt1_i32_b64 s17, s[24:25]
	s_nop 0
	v_mbcnt_lo_u32_b32 v99, s24, 0
	v_mbcnt_hi_u32_b32 v99, s25, v99
	v_cmp_gt_u32_e64 s[28:29], s16, v99
	s_and_b64 s[28:29], s[28:29], s[24:25]
	s_or_b64 s[26:27], s[26:27], s[28:29]
	s_sub_i32 s16, s16, s17
	s_max_i32 s16, s16, 0
	v_writelane_b32 v100, s26, 19
	v_writelane_b32 v101, s27, 19
	v_cmp_eq_u32_e64 s[24:25], s10, v52
	v_cmp_lt_u32_e64 s[26:27], s10, v52
	s_bcnt1_i32_b64 s17, s[24:25]
	s_nop 0
	v_mbcnt_lo_u32_b32 v99, s24, 0
	v_mbcnt_hi_u32_b32 v99, s25, v99
	v_cmp_gt_u32_e64 s[28:29], s16, v99
	s_and_b64 s[28:29], s[28:29], s[24:25]
	s_or_b64 s[26:27], s[26:27], s[28:29]
	s_sub_i32 s16, s16, s17
	s_max_i32 s16, s16, 0
	v_writelane_b32 v100, s26, 20
	v_writelane_b32 v101, s27, 20
	v_cmp_eq_u32_e64 s[24:25], s10, v53
	v_cmp_lt_u32_e64 s[26:27], s10, v53
	s_bcnt1_i32_b64 s17, s[24:25]
	s_nop 0
	v_mbcnt_lo_u32_b32 v99, s24, 0
	v_mbcnt_hi_u32_b32 v99, s25, v99
	v_cmp_gt_u32_e64 s[28:29], s16, v99
	s_and_b64 s[28:29], s[28:29], s[24:25]
	s_or_b64 s[26:27], s[26:27], s[28:29]
	s_sub_i32 s16, s16, s17
	s_max_i32 s16, s16, 0
	v_writelane_b32 v100, s26, 21
	v_writelane_b32 v101, s27, 21
	v_cmp_eq_u32_e64 s[24:25], s10, v54
	v_cmp_lt_u32_e64 s[26:27], s10, v54
	s_bcnt1_i32_b64 s17, s[24:25]
	s_nop 0
	v_mbcnt_lo_u32_b32 v99, s24, 0
	v_mbcnt_hi_u32_b32 v99, s25, v99
	v_cmp_gt_u32_e64 s[28:29], s16, v99
	s_and_b64 s[28:29], s[28:29], s[24:25]
	s_or_b64 s[26:27], s[26:27], s[28:29]
	s_sub_i32 s16, s16, s17
	s_max_i32 s16, s16, 0
	v_writelane_b32 v100, s26, 22
	v_writelane_b32 v101, s27, 22
	v_cmp_eq_u32_e64 s[24:25], s10, v55
	v_cmp_lt_u32_e64 s[26:27], s10, v55
	s_bcnt1_i32_b64 s17, s[24:25]
	s_nop 0
	v_mbcnt_lo_u32_b32 v99, s24, 0
	v_mbcnt_hi_u32_b32 v99, s25, v99
	v_cmp_gt_u32_e64 s[28:29], s16, v99
	s_and_b64 s[28:29], s[28:29], s[24:25]
	s_or_b64 s[26:27], s[26:27], s[28:29]
	s_sub_i32 s16, s16, s17
	s_max_i32 s16, s16, 0
	v_writelane_b32 v100, s26, 23
	v_writelane_b32 v101, s27, 23
	s_cmp_lt_u32 s21, 4
	s_cbranch_scc1 .Ltk_store
	v_cmp_eq_u32_e64 s[24:25], s10, v56
	v_cmp_lt_u32_e64 s[26:27], s10, v56
	s_bcnt1_i32_b64 s17, s[24:25]
	s_nop 0
	v_mbcnt_lo_u32_b32 v99, s24, 0
	v_mbcnt_hi_u32_b32 v99, s25, v99
	v_cmp_gt_u32_e64 s[28:29], s16, v99
	s_and_b64 s[28:29], s[28:29], s[24:25]
	s_or_b64 s[26:27], s[26:27], s[28:29]
	s_sub_i32 s16, s16, s17
	s_max_i32 s16, s16, 0
	v_writelane_b32 v100, s26, 24
	v_writelane_b32 v101, s27, 24
	v_cmp_eq_u32_e64 s[24:25], s10, v57
	v_cmp_lt_u32_e64 s[26:27], s10, v57
	s_bcnt1_i32_b64 s17, s[24:25]
	s_nop 0
	v_mbcnt_lo_u32_b32 v99, s24, 0
	v_mbcnt_hi_u32_b32 v99, s25, v99
	v_cmp_gt_u32_e64 s[28:29], s16, v99
	s_and_b64 s[28:29], s[28:29], s[24:25]
	s_or_b64 s[26:27], s[26:27], s[28:29]
	s_sub_i32 s16, s16, s17
	s_max_i32 s16, s16, 0
	v_writelane_b32 v100, s26, 25
	v_writelane_b32 v101, s27, 25
	v_cmp_eq_u32_e64 s[24:25], s10, v58
	v_cmp_lt_u32_e64 s[26:27], s10, v58
	s_bcnt1_i32_b64 s17, s[24:25]
	s_nop 0
	v_mbcnt_lo_u32_b32 v99, s24, 0
	v_mbcnt_hi_u32_b32 v99, s25, v99
	v_cmp_gt_u32_e64 s[28:29], s16, v99
	s_and_b64 s[28:29], s[28:29], s[24:25]
	s_or_b64 s[26:27], s[26:27], s[28:29]
	s_sub_i32 s16, s16, s17
	s_max_i32 s16, s16, 0
	v_writelane_b32 v100, s26, 26
	v_writelane_b32 v101, s27, 26
	v_cmp_eq_u32_e64 s[24:25], s10, v59
	v_cmp_lt_u32_e64 s[26:27], s10, v59
	s_bcnt1_i32_b64 s17, s[24:25]
	s_nop 0
	v_mbcnt_lo_u32_b32 v99, s24, 0
	v_mbcnt_hi_u32_b32 v99, s25, v99
	v_cmp_gt_u32_e64 s[28:29], s16, v99
	s_and_b64 s[28:29], s[28:29], s[24:25]
	s_or_b64 s[26:27], s[26:27], s[28:29]
	s_sub_i32 s16, s16, s17
	s_max_i32 s16, s16, 0
	v_writelane_b32 v100, s26, 27
	v_writelane_b32 v101, s27, 27
	v_cmp_eq_u32_e64 s[24:25], s10, v60
	v_cmp_lt_u32_e64 s[26:27], s10, v60
	s_bcnt1_i32_b64 s17, s[24:25]
	s_nop 0
	v_mbcnt_lo_u32_b32 v99, s24, 0
	v_mbcnt_hi_u32_b32 v99, s25, v99
	v_cmp_gt_u32_e64 s[28:29], s16, v99
	s_and_b64 s[28:29], s[28:29], s[24:25]
	s_or_b64 s[26:27], s[26:27], s[28:29]
	s_sub_i32 s16, s16, s17
	s_max_i32 s16, s16, 0
	v_writelane_b32 v100, s26, 28
	v_writelane_b32 v101, s27, 28
	v_cmp_eq_u32_e64 s[24:25], s10, v61
	v_cmp_lt_u32_e64 s[26:27], s10, v61
	s_bcnt1_i32_b64 s17, s[24:25]
	s_nop 0
	v_mbcnt_lo_u32_b32 v99, s24, 0
	v_mbcnt_hi_u32_b32 v99, s25, v99
	v_cmp_gt_u32_e64 s[28:29], s16, v99
	s_and_b64 s[28:29], s[28:29], s[24:25]
	s_or_b64 s[26:27], s[26:27], s[28:29]
	s_sub_i32 s16, s16, s17
	s_max_i32 s16, s16, 0
	v_writelane_b32 v100, s26, 29
	v_writelane_b32 v101, s27, 29
	v_cmp_eq_u32_e64 s[24:25], s10, v62
	v_cmp_lt_u32_e64 s[26:27], s10, v62
	s_bcnt1_i32_b64 s17, s[24:25]
	s_nop 0
	v_mbcnt_lo_u32_b32 v99, s24, 0
	v_mbcnt_hi_u32_b32 v99, s25, v99
	v_cmp_gt_u32_e64 s[28:29], s16, v99
	s_and_b64 s[28:29], s[28:29], s[24:25]
	s_or_b64 s[26:27], s[26:27], s[28:29]
	s_sub_i32 s16, s16, s17
	s_max_i32 s16, s16, 0
	v_writelane_b32 v100, s26, 30
	v_writelane_b32 v101, s27, 30
	v_cmp_eq_u32_e64 s[24:25], s10, v63
	v_cmp_lt_u32_e64 s[26:27], s10, v63
	s_bcnt1_i32_b64 s17, s[24:25]
	s_nop 0
	v_mbcnt_lo_u32_b32 v99, s24, 0
	v_mbcnt_hi_u32_b32 v99, s25, v99
	v_cmp_gt_u32_e64 s[28:29], s16, v99
	s_and_b64 s[28:29], s[28:29], s[24:25]
	s_or_b64 s[26:27], s[26:27], s[28:29]
	s_sub_i32 s16, s16, s17
	s_max_i32 s16, s16, 0
	v_writelane_b32 v100, s26, 31
	v_writelane_b32 v101, s27, 31
	s_branch .Ltk_store
